# stacked: s5-final diag(d) loads fetched once; attention bias loads no longer drain vmcnt each; adaLN matvec loads software-pipelined with plain fmac
# speedup vs baseline: 1.0061x; 1.0014x over previous
.LBB0_101:
	s_mul_hi_i32 s2, s16, 0x2aaaaaab
	s_lshr_b32 s3, s2, 31
	s_ashr_i32 s2, s2, 5
	s_add_i32 s20, s2, s3
	s_mul_i32 s2, s20, 0xc0
	s_sub_i32 s2, s16, s2
	s_lshl_b32 s6, s2, 6
	s_ashr_i32 s7, s6, 31
	s_mul_i32 s9, s20, 0x6000000
	s_lshl_b64 s[2:3], s[6:7], 2
	s_mul_hi_i32 s8, s20, 0x6000000
	s_add_u32 s2, s9, s2
	s_addc_u32 s3, s8, s3
	v_lshl_add_u64 v[12:13], v[10:11], 0, s[2:3]
	s_mov_b64 s[8:9], 0
	v_mov_b32_e32 v21, v20
	v_mov_b32_e32 v22, 0
	v_mov_b32_e32 v14, 0
	v_mov_b32_e32 v15, v9
	v_mov_b32_e32 v16, 0
	v_mov_b32_e32 v17, v9
	v_lshl_add_u64 v[24:25], v[12:13], 0, s[8:9]
	global_load_dword v64, v[24:25], off
	v_add_co_u32_e64 v26, s[2:3], s4, v24
	s_nop 1
	v_addc_co_u32_e64 v27, s[2:3], 0, v25, s[2:3]
	global_load_dword v66, v[26:27], off
	v_add_co_u32_e64 v28, s[2:3], s5, v24
	s_nop 1
	v_addc_co_u32_e64 v29, s[2:3], 0, v25, s[2:3]
	global_load_dword v68, v[28:29], off
	v_add_co_u32_e64 v30, s[2:3], s12, v24
	s_nop 1
	v_addc_co_u32_e64 v31, s[2:3], 0, v25, s[2:3]
	global_load_dword v70, v[30:31], off
	v_add_co_u32_e64 v32, s[2:3], s13, v24
	s_nop 1
	v_addc_co_u32_e64 v33, s[2:3], 0, v25, s[2:3]
	global_load_dword v72, v[32:33], off
	v_add_co_u32_e64 v34, s[2:3], s17, v24
	s_nop 1
	v_addc_co_u32_e64 v35, s[2:3], 0, v25, s[2:3]
	global_load_dword v74, v[34:35], off
	v_add_co_u32_e64 v36, s[2:3], s18, v24
	s_nop 1
	v_addc_co_u32_e64 v37, s[2:3], 0, v25, s[2:3]
	global_load_dword v76, v[36:37], off
	v_add_co_u32_e64 v24, s[2:3], s19, v24
	s_nop 1
	v_addc_co_u32_e64 v25, s[2:3], 0, v25, s[2:3]
	global_load_dword v78, v[24:25], off
	s_add_u32 s8, s8, 0x60000
	s_addc_u32 s9, s9, 0
.Lada_loop:
	v_lshl_add_u64 v[24:25], v[12:13], 0, s[8:9]
	global_load_dword v65, v[24:25], off
	v_add_co_u32_e64 v26, s[2:3], s4, v24
	s_nop 1
	v_addc_co_u32_e64 v27, s[2:3], 0, v25, s[2:3]
	global_load_dword v67, v[26:27], off
	v_add_co_u32_e64 v28, s[2:3], s5, v24
	s_nop 1
	v_addc_co_u32_e64 v29, s[2:3], 0, v25, s[2:3]
	global_load_dword v69, v[28:29], off
	v_add_co_u32_e64 v30, s[2:3], s12, v24
	s_nop 1
	v_addc_co_u32_e64 v31, s[2:3], 0, v25, s[2:3]
	global_load_dword v71, v[30:31], off
	v_add_co_u32_e64 v32, s[2:3], s13, v24
	s_nop 1
	v_addc_co_u32_e64 v33, s[2:3], 0, v25, s[2:3]
	global_load_dword v73, v[32:33], off
	v_add_co_u32_e64 v34, s[2:3], s17, v24
	s_nop 1
	v_addc_co_u32_e64 v35, s[2:3], 0, v25, s[2:3]
	global_load_dword v75, v[34:35], off
	v_add_co_u32_e64 v36, s[2:3], s18, v24
	s_nop 1
	v_addc_co_u32_e64 v37, s[2:3], 0, v25, s[2:3]
	global_load_dword v77, v[36:37], off
	v_add_co_u32_e64 v24, s[2:3], s19, v24
	s_nop 1
	v_addc_co_u32_e64 v25, s[2:3], 0, v25, s[2:3]
	global_load_dword v79, v[24:25], off
	s_add_u32 s8, s8, 0x60000
	s_addc_u32 s9, s9, 0
	ds_read_b128 v[24:27], v21
	ds_read_b128 v[28:31], v21 offset:16
	ds_read_b128 v[32:35], v21 offset:8192
	ds_read_b128 v[36:39], v21 offset:8208
	ds_read_b128 v[40:43], v21 offset:16384
	ds_read_b128 v[44:47], v21 offset:16400
	ds_read_b128 v[48:51], v21 offset:24576
	ds_read_b128 v[52:55], v21 offset:24592
	ds_read_b128 v[56:59], v21 offset:32768
	ds_read_b128 v[60:63], v21 offset:32784
	v_add_u32_e32 v21, 32, v21
	s_waitcnt vmcnt(8)
	s_waitcnt lgkmcnt(0)
	v_fmac_f32_e32 v22, v64, v24
	v_fmac_f32_e32 v17, v64, v32
	v_fmac_f32_e32 v16, v64, v40
	v_fmac_f32_e32 v15, v64, v48
	v_fmac_f32_e32 v14, v64, v56
	v_fmac_f32_e32 v22, v66, v25
	v_fmac_f32_e32 v17, v66, v33
	v_fmac_f32_e32 v16, v66, v41
	v_fmac_f32_e32 v15, v66, v49
	v_fmac_f32_e32 v14, v66, v57
	v_fmac_f32_e32 v22, v68, v26
	v_fmac_f32_e32 v17, v68, v34
	v_fmac_f32_e32 v16, v68, v42
	v_fmac_f32_e32 v15, v68, v50
	v_fmac_f32_e32 v14, v68, v58
	v_fmac_f32_e32 v22, v70, v27
	v_fmac_f32_e32 v17, v70, v35
	v_fmac_f32_e32 v16, v70, v43
	v_fmac_f32_e32 v15, v70, v51
	v_fmac_f32_e32 v14, v70, v59
	v_fmac_f32_e32 v22, v72, v28
	v_fmac_f32_e32 v17, v72, v36
	v_fmac_f32_e32 v16, v72, v44
	v_fmac_f32_e32 v15, v72, v52
	v_fmac_f32_e32 v14, v72, v60
	v_fmac_f32_e32 v22, v74, v29
	v_fmac_f32_e32 v17, v74, v37
	v_fmac_f32_e32 v16, v74, v45
	v_fmac_f32_e32 v15, v74, v53
	v_fmac_f32_e32 v14, v74, v61
	v_fmac_f32_e32 v22, v76, v30
	v_fmac_f32_e32 v17, v76, v38
	v_fmac_f32_e32 v16, v76, v46
	v_fmac_f32_e32 v15, v76, v54
	v_fmac_f32_e32 v14, v76, v62
	v_fmac_f32_e32 v22, v78, v31
	v_fmac_f32_e32 v17, v78, v39
	v_fmac_f32_e32 v16, v78, v47
	v_fmac_f32_e32 v15, v78, v55
	v_fmac_f32_e32 v14, v78, v63
	s_cmp_eq_u32 s8, 0xc00000
	s_cbranch_scc1 .Lada_last
	v_lshl_add_u64 v[24:25], v[12:13], 0, s[8:9]
	global_load_dword v64, v[24:25], off
	v_add_co_u32_e64 v26, s[2:3], s4, v24
	s_nop 1
	v_addc_co_u32_e64 v27, s[2:3], 0, v25, s[2:3]
	global_load_dword v66, v[26:27], off
	v_add_co_u32_e64 v28, s[2:3], s5, v24
	s_nop 1
	v_addc_co_u32_e64 v29, s[2:3], 0, v25, s[2:3]
	global_load_dword v68, v[28:29], off
	v_add_co_u32_e64 v30, s[2:3], s12, v24
	s_nop 1
	v_addc_co_u32_e64 v31, s[2:3], 0, v25, s[2:3]
	global_load_dword v70, v[30:31], off
	v_add_co_u32_e64 v32, s[2:3], s13, v24
	s_nop 1
	v_addc_co_u32_e64 v33, s[2:3], 0, v25, s[2:3]
	global_load_dword v72, v[32:33], off
	v_add_co_u32_e64 v34, s[2:3], s17, v24
	s_nop 1
	v_addc_co_u32_e64 v35, s[2:3], 0, v25, s[2:3]
	global_load_dword v74, v[34:35], off
	v_add_co_u32_e64 v36, s[2:3], s18, v24
	s_nop 1
	v_addc_co_u32_e64 v37, s[2:3], 0, v25, s[2:3]
	global_load_dword v76, v[36:37], off
	v_add_co_u32_e64 v24, s[2:3], s19, v24
	s_nop 1
	v_addc_co_u32_e64 v25, s[2:3], 0, v25, s[2:3]
	global_load_dword v78, v[24:25], off
	s_add_u32 s8, s8, 0x60000
	s_addc_u32 s9, s9, 0
	ds_read_b128 v[24:27], v21
	ds_read_b128 v[28:31], v21 offset:16
	ds_read_b128 v[32:35], v21 offset:8192
	ds_read_b128 v[36:39], v21 offset:8208
	ds_read_b128 v[40:43], v21 offset:16384
	ds_read_b128 v[44:47], v21 offset:16400
	ds_read_b128 v[48:51], v21 offset:24576
	ds_read_b128 v[52:55], v21 offset:24592
	ds_read_b128 v[56:59], v21 offset:32768
	ds_read_b128 v[60:63], v21 offset:32784
	v_add_u32_e32 v21, 32, v21
	s_waitcnt vmcnt(8)
	s_waitcnt lgkmcnt(0)
	v_fmac_f32_e32 v22, v65, v24
	v_fmac_f32_e32 v17, v65, v32
	v_fmac_f32_e32 v16, v65, v40
	v_fmac_f32_e32 v15, v65, v48
	v_fmac_f32_e32 v14, v65, v56
	v_fmac_f32_e32 v22, v67, v25
	v_fmac_f32_e32 v17, v67, v33
	v_fmac_f32_e32 v16, v67, v41
	v_fmac_f32_e32 v15, v67, v49
	v_fmac_f32_e32 v14, v67, v57
	v_fmac_f32_e32 v22, v69, v26
	v_fmac_f32_e32 v17, v69, v34
	v_fmac_f32_e32 v16, v69, v42
	v_fmac_f32_e32 v15, v69, v50
	v_fmac_f32_e32 v14, v69, v58
	v_fmac_f32_e32 v22, v71, v27
	v_fmac_f32_e32 v17, v71, v35
	v_fmac_f32_e32 v16, v71, v43
	v_fmac_f32_e32 v15, v71, v51
	v_fmac_f32_e32 v14, v71, v59
	v_fmac_f32_e32 v22, v73, v28
	v_fmac_f32_e32 v17, v73, v36
	v_fmac_f32_e32 v16, v73, v44
	v_fmac_f32_e32 v15, v73, v52
	v_fmac_f32_e32 v14, v73, v60
	v_fmac_f32_e32 v22, v75, v29
	v_fmac_f32_e32 v17, v75, v37
	v_fmac_f32_e32 v16, v75, v45
	v_fmac_f32_e32 v15, v75, v53
	v_fmac_f32_e32 v14, v75, v61
	v_fmac_f32_e32 v22, v77, v30
	v_fmac_f32_e32 v17, v77, v38
	v_fmac_f32_e32 v16, v77, v46
	v_fmac_f32_e32 v15, v77, v54
	v_fmac_f32_e32 v14, v77, v62
	v_fmac_f32_e32 v22, v79, v31
	v_fmac_f32_e32 v17, v79, v39
	v_fmac_f32_e32 v16, v79, v47
	v_fmac_f32_e32 v15, v79, v55
	v_fmac_f32_e32 v14, v79, v63
	s_branch .Lada_loop
.Lada_last:
	ds_read_b128 v[24:27], v21
	ds_read_b128 v[28:31], v21 offset:16
	ds_read_b128 v[32:35], v21 offset:8192
	ds_read_b128 v[36:39], v21 offset:8208
	ds_read_b128 v[40:43], v21 offset:16384
	ds_read_b128 v[44:47], v21 offset:16400
	ds_read_b128 v[48:51], v21 offset:24576
	ds_read_b128 v[52:55], v21 offset:24592
	ds_read_b128 v[56:59], v21 offset:32768
	ds_read_b128 v[60:63], v21 offset:32784
	v_add_u32_e32 v21, 32, v21
	s_waitcnt vmcnt(0)
	s_waitcnt lgkmcnt(0)
	v_fmac_f32_e32 v22, v65, v24
	v_fmac_f32_e32 v17, v65, v32
	v_fmac_f32_e32 v16, v65, v40
	v_fmac_f32_e32 v15, v65, v48
	v_fmac_f32_e32 v14, v65, v56
	v_fmac_f32_e32 v22, v67, v25
	v_fmac_f32_e32 v17, v67, v33
	v_fmac_f32_e32 v16, v67, v41
	v_fmac_f32_e32 v15, v67, v49
	v_fmac_f32_e32 v14, v67, v57
	v_fmac_f32_e32 v22, v69, v26
	v_fmac_f32_e32 v17, v69, v34
	v_fmac_f32_e32 v16, v69, v42
	v_fmac_f32_e32 v15, v69, v50
	v_fmac_f32_e32 v14, v69, v58
	v_fmac_f32_e32 v22, v71, v27
	v_fmac_f32_e32 v17, v71, v35
	v_fmac_f32_e32 v16, v71, v43
	v_fmac_f32_e32 v15, v71, v51
	v_fmac_f32_e32 v14, v71, v59
	v_fmac_f32_e32 v22, v73, v28
	v_fmac_f32_e32 v17, v73, v36
	v_fmac_f32_e32 v16, v73, v44
	v_fmac_f32_e32 v15, v73, v52
	v_fmac_f32_e32 v14, v73, v60
	v_fmac_f32_e32 v22, v75, v29
	v_fmac_f32_e32 v17, v75, v37
	v_fmac_f32_e32 v16, v75, v45
	v_fmac_f32_e32 v15, v75, v53
	v_fmac_f32_e32 v14, v75, v61
	v_fmac_f32_e32 v22, v77, v30
	v_fmac_f32_e32 v17, v77, v38
	v_fmac_f32_e32 v16, v77, v46
	v_fmac_f32_e32 v15, v77, v54
	v_fmac_f32_e32 v14, v77, v62
	v_fmac_f32_e32 v22, v79, v31
	v_fmac_f32_e32 v17, v79, v39
	v_fmac_f32_e32 v16, v79, v47
	v_fmac_f32_e32 v15, v79, v55
	v_fmac_f32_e32 v14, v79, v63
	ds_write_b32 v18, v22 offset:40960
	ds_write2st64_b32 v19, v17, v16 offset0:161 offset1:162
	ds_write2st64_b32 v19, v15, v14 offset0:163 offset1:164
	s_waitcnt lgkmcnt(0)
	s_barrier
	s_and_saveexec_b64 s[2:3], vcc
	s_cbranch_execz .LBB0_100
	s_mul_i32 s8, s20, 0x3000
	s_add_i32 s8, s8, s6
	v_or_b32_e32 v12, s8, v4
	v_ashrrev_i32_e32 v13, 31, v12
	v_lshl_add_u64 v[12:13], v[12:13], 2, s[10:11]
	global_load_dword v21, v[12:13], off
	v_add_u32_e32 v24, v1, v5
	ds_read2st64_b32 v[14:15], v24 offset0:160 offset1:165
	ds_read2st64_b32 v[16:17], v24 offset0:170 offset1:175
	ds_read2st64_b32 v[22:23], v24 offset0:180 offset1:185
	ds_read2st64_b32 v[24:25], v24 offset0:190 offset1:195
	v_mad_i64_i32 v[12:13], s[8:9], s20, 5, v[6:7]
	v_mad_u64_u32 v[26:27], s[8:9], v12, s4, v[2:3]
	v_mad_i32_i24 v27, v13, s4, v27
	v_lshl_add_u64 v[12:13], s[6:7], 2, v[26:27]
	v_lshl_add_u64 v[12:13], v[12:13], 0, v[8:9]
	s_waitcnt vmcnt(0) lgkmcnt(3)
	v_add_f32_e32 v14, v21, v14
	v_add_f32_e32 v14, v14, v15
	s_waitcnt lgkmcnt(2)
	v_add_f32_e32 v14, v14, v16
	v_add_f32_e32 v14, v14, v17
	s_waitcnt lgkmcnt(1)
	v_add_f32_e32 v14, v14, v22
	v_add_f32_e32 v14, v14, v23
	s_waitcnt lgkmcnt(0)
	v_add_f32_e32 v14, v14, v24
	v_add_f32_e32 v14, v14, v25
	global_store_dword v[12:13], v14, off
	s_branch .LBB0_100

.LBB0_462:
	s_waitcnt vmcnt(0)
	s_add_i32 s4, s36, -1
	s_cmp_lt_u32 s4, 4
	s_cselect_b64 s[18:19], -1, 0
	s_cmp_gt_u32 s4, 3
	s_cselect_b64 s[24:25], -1, 0
	v_cndmask_b32_e64 v60, 0, 1, s[50:51]
	s_mov_b64 s[22:23], -1
	s_and_b64 vcc, exec, s[24:25]
	v_cmp_ne_u32_e64 s[20:21], 1, v60
	s_cbranch_vccz .LBB0_467
	s_and_b64 vcc, exec, s[20:21]
	s_cbranch_vccnz .LBB0_703
	s_mov_b64 s[22:23], src_shared_base
	v_add_u32_e32 v60, 0, v196
	v_add_u32_e32 v60, 0xde00, v60
	v_mov_b32_e32 v61, s23
	s_cbranch_execnz .LBB0_466

.LBB0_518:
	flat_load_dwordx4 v[120:123], v[60:61]
	v_cndmask_b32_e64 v60, 0, 1, s[18:19]
	v_mov_b32_e32 v156, 0
	v_cmp_ne_u32_e64 s[24:25], 1, v60
	s_andn2_b64 vcc, exec, s[18:19]
	v_add_u32_e32 v204, s90, v195
	v_mov_b32_e32 v157, 0
	s_cbranch_vccnz .LBB0_520
	v_add_u32_e32 v60, 0xd9, v204
	v_ashrrev_i32_e32 v61, 31, v60
	s_nop 0
	v_lshl_add_u64 v[60:61], v[60:61], 2, v[134:135]
	flat_load_dword v157, v[60:61]
.LBB0_520:
	s_and_b64 vcc, exec, s[24:25]
	v_add_u32_e32 v205, s90, v194
	s_cbranch_vccnz .LBB0_522
	v_add_u32_e32 v60, 0xd9, v205
	v_ashrrev_i32_e32 v61, 31, v60
	s_nop 0
	v_lshl_add_u64 v[60:61], v[60:61], 2, v[134:135]
	flat_load_dword v156, v[60:61]
.LBB0_522:
	v_mov_b32_e32 v158, 0
	s_and_b64 vcc, exec, s[24:25]
	v_add_u32_e32 v206, s90, v193
	v_mov_b32_e32 v159, 0
	s_cbranch_vccnz .LBB0_524
	v_add_u32_e32 v60, 0xd9, v206
	v_ashrrev_i32_e32 v61, 31, v60
	s_nop 0
	v_lshl_add_u64 v[60:61], v[60:61], 2, v[134:135]
	flat_load_dword v159, v[60:61]
.LBB0_524:
	s_and_b64 vcc, exec, s[24:25]
	v_add_u32_e32 v207, s90, v192
	s_cbranch_vccnz .LBB0_526
	v_add_u32_e32 v60, 0xd9, v207
	v_ashrrev_i32_e32 v61, 31, v60
	s_nop 0
	v_lshl_add_u64 v[60:61], v[60:61], 2, v[134:135]
	flat_load_dword v158, v[60:61]
.LBB0_526:
	v_mov_b32_e32 v160, 0
	s_and_b64 vcc, exec, s[24:25]
	v_add_u32_e32 v208, s90, v191
	v_mov_b32_e32 v161, 0
	s_cbranch_vccnz .LBB0_528
	v_add_u32_e32 v60, 0xd9, v208
	v_ashrrev_i32_e32 v61, 31, v60
	s_nop 0
	v_lshl_add_u64 v[60:61], v[60:61], 2, v[134:135]
	flat_load_dword v161, v[60:61]
.LBB0_528:
	s_and_b64 vcc, exec, s[24:25]
	v_add_u32_e32 v209, s90, v188
	s_cbranch_vccnz .LBB0_530
	v_add_u32_e32 v60, 0xd9, v209
	v_ashrrev_i32_e32 v61, 31, v60
	s_nop 0
	v_lshl_add_u64 v[60:61], v[60:61], 2, v[134:135]
	flat_load_dword v160, v[60:61]
.LBB0_530:
	v_mov_b32_e32 v162, 0
	s_and_b64 vcc, exec, s[24:25]
	v_add_u32_e32 v210, s90, v187
	v_mov_b32_e32 v163, 0
	s_cbranch_vccnz .LBB0_540
	v_add_u32_e32 v60, 0xd9, v210
	v_ashrrev_i32_e32 v61, 31, v60
	s_nop 0
	v_lshl_add_u64 v[60:61], v[60:61], 2, v[134:135]
	flat_load_dword v163, v[60:61]
	s_and_b64 vcc, exec, s[24:25]
	v_add_u32_e32 v211, s90, v186
	s_cbranch_vccz .LBB0_541

.LBB0_533:
	v_add_u32_e32 v60, 0xf8, v204
	v_ashrrev_i32_e32 v61, 31, v60
	s_nop 0
	v_lshl_add_u64 v[60:61], v[60:61], 2, v[134:135]
	flat_load_dword v165, v[60:61]
	s_and_b64 vcc, exec, s[24:25]
	s_cbranch_vccz .LBB0_543

.LBB0_535:
	v_add_u32_e32 v60, 0xf8, v206
	v_ashrrev_i32_e32 v61, 31, v60
	s_nop 0
	v_lshl_add_u64 v[60:61], v[60:61], 2, v[134:135]
	flat_load_dword v167, v[60:61]
	s_and_b64 vcc, exec, s[24:25]
	s_cbranch_vccz .LBB0_545

.LBB0_537:
	v_add_u32_e32 v60, 0xf8, v208
	v_ashrrev_i32_e32 v61, 31, v60
	s_nop 0
	v_lshl_add_u64 v[60:61], v[60:61], 2, v[134:135]
	flat_load_dword v174, v[60:61]
	s_and_b64 vcc, exec, s[24:25]
	s_cbranch_vccz .LBB0_547

.LBB0_539:
	v_add_u32_e32 v60, 0xf8, v210
	v_ashrrev_i32_e32 v61, 31, v60
	s_nop 0
	v_lshl_add_u64 v[60:61], v[60:61], 2, v[134:135]
	flat_load_dword v176, v[60:61]
	s_and_b64 vcc, exec, s[24:25]
	s_cbranch_vccz .LBB0_549
	s_branch .LBB0_550

.LBB0_541:
	v_add_u32_e32 v60, 0xd9, v211
	v_ashrrev_i32_e32 v61, 31, v60
	s_nop 0
	v_lshl_add_u64 v[60:61], v[60:61], 2, v[134:135]
	flat_load_dword v162, v[60:61]
	v_mov_b32_e32 v164, 0
	s_and_b64 vcc, exec, s[24:25]
	v_mov_b32_e32 v165, 0
	s_cbranch_vccz .LBB0_533

.LBB0_543:
	v_add_u32_e32 v60, 0xf8, v205
	v_ashrrev_i32_e32 v61, 31, v60
	s_nop 0
	v_lshl_add_u64 v[60:61], v[60:61], 2, v[134:135]
	flat_load_dword v164, v[60:61]
	v_mov_b32_e32 v166, 0
	s_and_b64 vcc, exec, s[24:25]
	v_mov_b32_e32 v167, 0
	s_cbranch_vccz .LBB0_535

.LBB0_545:
	v_add_u32_e32 v60, 0xf8, v207
	v_ashrrev_i32_e32 v61, 31, v60
	s_nop 0
	v_lshl_add_u64 v[60:61], v[60:61], 2, v[134:135]
	flat_load_dword v166, v[60:61]
	v_mov_b32_e32 v173, 0
	s_and_b64 vcc, exec, s[24:25]
	v_mov_b32_e32 v174, 0
	s_cbranch_vccz .LBB0_537

.LBB0_547:
	v_add_u32_e32 v60, 0xf8, v209
	v_ashrrev_i32_e32 v61, 31, v60
	s_nop 0
	v_lshl_add_u64 v[60:61], v[60:61], 2, v[134:135]
	flat_load_dword v173, v[60:61]
	v_mov_b32_e32 v175, 0
	s_and_b64 vcc, exec, s[24:25]
	v_mov_b32_e32 v176, 0
	s_cbranch_vccz .LBB0_539

.LBB0_549:
	v_add_u32_e32 v60, 0xf8, v211
	v_ashrrev_i32_e32 v61, 31, v60
	s_nop 0
	v_lshl_add_u64 v[60:61], v[60:61], 2, v[134:135]
	flat_load_dword v175, v[60:61]

.LBB0_794:
	s_or_b64 exec, exec, s[10:11]
	v_bfe_u32 v123, v34, 4, 2
	v_lshlrev_b32_e32 v2, 3, v123
	v_lshlrev_b32_e32 v3, 4, v124
	v_or_b32_e32 v126, v122, v3
	v_mov_b32_e32 v127, v1
	v_lshrrev_b32_e32 v40, 3, v122
	v_mov_b32_e32 v32, 0
	v_cmp_eq_u32_e32 vcc, v40, v123
	v_mov_b32_e32 v0, 0
	v_mov_b32_e32 v33, 0
	s_and_b64 s[4:5], s[0:1], vcc
	v_mov_b32_e32 v34, 0
	v_mov_b32_e32 v35, 0
	v_mov_b32_e32 v37, 0
	v_mov_b32_e32 v38, 0
	v_mov_b32_e32 v39, 0
	s_and_saveexec_b64 s[10:11], s[4:5]
	s_cbranch_execz .Ls5f_dsk_done
	global_load_dwordx2 v[40:41], v1, s[16:17]
	s_waitcnt vmcnt(0)
	v_lshl_add_u64 v[40:41], v[126:127], 2, v[40:41]
	global_load_dword v41, v[40:41], off
	v_and_b32_e32 v40, 7, v122
	v_cmp_eq_u32_e64 s[4:5], 0, v40
	v_cmp_eq_u32_e32 vcc, 1, v40
	s_waitcnt vmcnt(0)
	s_nop 0
	v_cndmask_b32_e64 v32, v32, v41, s[4:5]
	v_cndmask_b32_e32 v0, v0, v41, vcc
	v_cmp_eq_u32_e64 s[4:5], 2, v40
	v_cmp_eq_u32_e32 vcc, 3, v40
	s_nop 1
	v_cndmask_b32_e64 v34, v34, v41, s[4:5]
	v_cndmask_b32_e32 v33, v33, v41, vcc
	v_cmp_eq_u32_e64 s[4:5], 4, v40
	v_cmp_eq_u32_e32 vcc, 5, v40
	s_nop 1
	v_cndmask_b32_e64 v37, v37, v41, s[4:5]
	v_cndmask_b32_e32 v35, v35, v41, vcc
	v_cmp_eq_u32_e64 s[4:5], 6, v40
	v_cmp_eq_u32_e32 vcc, 7, v40
	s_nop 1
	v_cndmask_b32_e64 v39, v39, v41, s[4:5]
	v_cndmask_b32_e32 v38, v38, v41, vcc
